# fused diff attention v5: next-tile LDS-DMA issue moved behind the QK MFMAs (K fragment reads no longer queue behind the DMA issue after the barrier)
# speedup vs baseline: 1.0556x; 1.0063x over previous
; __device__ __forceinline__ void cmask(f32x16&p0,f32x16&p1,int jb,int qrel,int hi,int wrow){
;   const float NEG=-INFINITY; int kb=64*jb+4*hi;
;   if(64*jb+63<=wrow) return;
;   if(64*jb>wrow+31){
;     #pragma unroll
;     for(int r=0;r<16;++r){p0[r]=NEG;p1[r]=NEG;}
;     return; }
;   #pragma unroll
;   for(int r=0;r<16;++r){int kv=kb+(r&3)+8*(r>>2); if(kv>qrel)p0[r]=NEG; if(kv+32>qrel)p1[r]=NEG;}
.Lfd_loop:
	s_waitcnt vmcnt(3)
	s_barrier
	s_add_i32 s94, s88, 3
	s_add_i32 s0, s89, -1
	s_min_i32 s94, s94, s0
	s_lshl_b32 s0, s88, 6
	s_cmp_gt_i32 s0, s23
	s_cbranch_scc0 .Lfd_work
	s_lshl_b32 s0, s94, 16
	s_add_u32 s44, s80, s0
	s_addc_u32 s45, s81, 0
	s_add_u32 s46, s82, s0
	s_addc_u32 s47, s83, 0
	s_and_b32 s1, s94, 3
	s_lshl_b32 s1, s1, 13
	s_lshl_b32 s2, s1, 1
	s_add_i32 s1, s1, s29
	s_mov_b32 m0, s1
	s_add_i32 s2, s2, s29
	global_load_lds_dwordx4 v10, s[44:45]
	s_add_i32 s2, s2, 0x8000
	s_mov_b32 m0, s2
	s_add_i32 s2, s2, 0x2000
	global_load_lds_dwordx4 v11, s[46:47]
	s_mov_b32 m0, s2
	s_nop 0
	global_load_lds_dwordx4 v12, s[46:47]
	s_branch .Lfd_next
.Lfd_work:
	s_and_b32 s0, s88, 3
	s_lshl_b32 s0, s0, 13
	v_add_u32_e32 v14, s0, v13
	ds_read_b128 v[176:179], v14 offset:0
	ds_read_b128 v[180:183], v14 offset:512
	ds_read_b128 v[184:187], v14 offset:2048
	ds_read_b128 v[188:191], v14 offset:2560
	ds_read_b128 v[192:195], v14 offset:4096
	ds_read_b128 v[196:199], v14 offset:4608
	ds_read_b128 v[200:203], v14 offset:6144
	ds_read_b128 v[204:207], v14 offset:6656
	s_and_b32 s0, s88, 3
	s_lshl_b32 s0, s0, 14
	v_add_u32_e32 v32, s0, v15
	s_waitcnt lgkmcnt(6)
	v_mfma_f32_32x32x16_bf16 v[112:127], v[176:179], v[160:163], v[144:159]
	ds_read_b64_tr_b16 v[220:221], v32 offset:8192
	ds_read_b64_tr_b16 v[222:223], v32 offset:8704
	v_mfma_f32_32x32x16_bf16 v[128:143], v[180:183], v[160:163], v[144:159]
	ds_read_b64_tr_b16 v[224:225], v32 offset:9216
	ds_read_b64_tr_b16 v[226:227], v32 offset:9728
	s_waitcnt lgkmcnt(8)
	v_mfma_f32_32x32x16_bf16 v[112:127], v[184:187], v[164:167], v[112:127]
	ds_read_b64_tr_b16 v[228:229], v32 offset:10240
	ds_read_b64_tr_b16 v[230:231], v32 offset:10752
	v_mfma_f32_32x32x16_bf16 v[128:143], v[188:191], v[164:167], v[128:143]
	ds_read_b64_tr_b16 v[232:233], v32 offset:11264
	ds_read_b64_tr_b16 v[234:235], v32 offset:11776
	s_waitcnt lgkmcnt(10)
	v_mfma_f32_32x32x16_bf16 v[112:127], v[192:195], v[168:171], v[112:127]
	ds_read_b64_tr_b16 v[236:237], v32 offset:12288
	ds_read_b64_tr_b16 v[238:239], v32 offset:12800
	v_mfma_f32_32x32x16_bf16 v[128:143], v[196:199], v[168:171], v[128:143]
	ds_read_b64_tr_b16 v[240:241], v32 offset:13312
	ds_read_b64_tr_b16 v[242:243], v32 offset:13824
	s_waitcnt lgkmcnt(12)
	v_mfma_f32_32x32x16_bf16 v[112:127], v[200:203], v[172:175], v[112:127]
	ds_read_b64_tr_b16 v[244:245], v32 offset:14336
	ds_read_b64_tr_b16 v[246:247], v32 offset:14848
	v_mfma_f32_32x32x16_bf16 v[128:143], v[204:207], v[172:175], v[128:143]
	ds_read_b64_tr_b16 v[248:249], v32 offset:15360
	ds_read_b64_tr_b16 v[250:251], v32 offset:15872
	ds_read_b64_tr_b16 v[176:177], v32 offset:0
	ds_read_b64_tr_b16 v[178:179], v32 offset:512
	ds_read_b64_tr_b16 v[180:181], v32 offset:1024
	ds_read_b64_tr_b16 v[182:183], v32 offset:1536
	ds_read_b64_tr_b16 v[184:185], v32 offset:2048
	ds_read_b64_tr_b16 v[186:187], v32 offset:2560
	ds_read_b64_tr_b16 v[188:189], v32 offset:3072
	ds_read_b64_tr_b16 v[190:191], v32 offset:3584
	ds_read_b64_tr_b16 v[192:193], v32 offset:4096
	ds_read_b64_tr_b16 v[194:195], v32 offset:4608
	ds_read_b64_tr_b16 v[196:197], v32 offset:5120
	ds_read_b64_tr_b16 v[198:199], v32 offset:5632
	ds_read_b64_tr_b16 v[200:201], v32 offset:6144
	ds_read_b64_tr_b16 v[202:203], v32 offset:6656
	ds_read_b64_tr_b16 v[204:205], v32 offset:7168
	ds_read_b64_tr_b16 v[206:207], v32 offset:7680
	s_lshl_b32 s0, s94, 16
	s_add_u32 s44, s80, s0
	s_addc_u32 s45, s81, 0
	s_add_u32 s46, s82, s0
	s_addc_u32 s47, s83, 0
	s_and_b32 s1, s94, 3
	s_lshl_b32 s1, s1, 13
	s_lshl_b32 s2, s1, 1
	s_add_i32 s1, s1, s29
	s_mov_b32 m0, s1
	s_add_i32 s2, s2, s29
	global_load_lds_dwordx4 v10, s[44:45]
	s_add_i32 s2, s2, 0x8000
	s_mov_b32 m0, s2
	s_add_i32 s2, s2, 0x2000
	global_load_lds_dwordx4 v11, s[46:47]
	s_mov_b32 m0, s2
	s_nop 0
	global_load_lds_dwordx4 v12, s[46:47]
	s_lshl_b32 s0, s88, 6
	s_add_i32 s1, s0, 63
	s_cmp_le_i32 s1, s22
	s_cbranch_scc1 .Lfd_nomaskA
	v_subrev_u32_e32 v4, s0, v33
	v_cmp_gt_i32_e64 s[36:37], 0, v4
	v_cmp_gt_i32_e64 s[38:39], 1, v4
	v_cmp_gt_i32_e64 s[48:49], 2, v4
	v_cmp_gt_i32_e64 s[50:51], 3, v4
	v_cndmask_b32_e64 v112, v112, v47, s[36:37]
	v_cndmask_b32_e64 v113, v113, v47, s[38:39]
	v_cndmask_b32_e64 v114, v114, v47, s[48:49]
	v_cndmask_b32_e64 v115, v115, v47, s[50:51]
	v_cmp_gt_i32_e64 s[36:37], 8, v4
	v_cmp_gt_i32_e64 s[38:39], 9, v4
	v_cmp_gt_i32_e64 s[48:49], 10, v4
	v_cmp_gt_i32_e64 s[50:51], 11, v4
	v_cndmask_b32_e64 v116, v116, v47, s[36:37]
	v_cndmask_b32_e64 v117, v117, v47, s[38:39]
	v_cndmask_b32_e64 v118, v118, v47, s[48:49]
	v_cndmask_b32_e64 v119, v119, v47, s[50:51]
	v_cmp_gt_i32_e64 s[36:37], 16, v4
	v_cmp_gt_i32_e64 s[38:39], 17, v4
	v_cmp_gt_i32_e64 s[48:49], 18, v4
	v_cmp_gt_i32_e64 s[50:51], 19, v4
	v_cndmask_b32_e64 v120, v120, v47, s[36:37]
	v_cndmask_b32_e64 v121, v121, v47, s[38:39]
	v_cndmask_b32_e64 v122, v122, v47, s[48:49]
	v_cndmask_b32_e64 v123, v123, v47, s[50:51]
	v_cmp_gt_i32_e64 s[36:37], 24, v4
	v_cmp_gt_i32_e64 s[38:39], 25, v4
	v_cmp_gt_i32_e64 s[48:49], 26, v4
	v_cmp_gt_i32_e64 s[50:51], 27, v4
	v_cndmask_b32_e64 v124, v124, v47, s[36:37]
	v_cndmask_b32_e64 v125, v125, v47, s[38:39]
	v_cndmask_b32_e64 v126, v126, v47, s[48:49]
	v_cndmask_b32_e64 v127, v127, v47, s[50:51]
	v_cmp_gt_i32_e64 s[36:37], 32, v4
	v_cmp_gt_i32_e64 s[38:39], 33, v4
	v_cmp_gt_i32_e64 s[48:49], 34, v4
	v_cmp_gt_i32_e64 s[50:51], 35, v4
	v_cndmask_b32_e64 v128, v128, v47, s[36:37]
	v_cndmask_b32_e64 v129, v129, v47, s[38:39]
	v_cndmask_b32_e64 v130, v130, v47, s[48:49]
	v_cndmask_b32_e64 v131, v131, v47, s[50:51]
	v_cmp_gt_i32_e64 s[36:37], 40, v4
	v_cmp_gt_i32_e64 s[38:39], 41, v4
	v_cmp_gt_i32_e64 s[48:49], 42, v4
	v_cmp_gt_i32_e64 s[50:51], 43, v4
	v_cndmask_b32_e64 v132, v132, v47, s[36:37]
	v_cndmask_b32_e64 v133, v133, v47, s[38:39]
	v_cndmask_b32_e64 v134, v134, v47, s[48:49]
	v_cndmask_b32_e64 v135, v135, v47, s[50:51]
	v_cmp_gt_i32_e64 s[36:37], 48, v4
	v_cmp_gt_i32_e64 s[38:39], 49, v4
	v_cmp_gt_i32_e64 s[48:49], 50, v4
	v_cmp_gt_i32_e64 s[50:51], 51, v4
	v_cndmask_b32_e64 v136, v136, v47, s[36:37]
	v_cndmask_b32_e64 v137, v137, v47, s[38:39]
	v_cndmask_b32_e64 v138, v138, v47, s[48:49]
	v_cndmask_b32_e64 v139, v139, v47, s[50:51]
	v_cmp_gt_i32_e64 s[36:37], 56, v4
	v_cmp_gt_i32_e64 s[38:39], 57, v4
	v_cmp_gt_i32_e64 s[48:49], 58, v4
	v_cmp_gt_i32_e64 s[50:51], 59, v4
	v_cndmask_b32_e64 v140, v140, v47, s[36:37]
	v_cndmask_b32_e64 v141, v141, v47, s[38:39]
	v_cndmask_b32_e64 v142, v142, v47, s[48:49]
	v_cndmask_b32_e64 v143, v143, v47, s[50:51]
